# split-phase barrier build + sample GEMM write-through stores / sub-barrier without L2 write-back
# speedup vs baseline: 1.0052x; 1.0052x over previous
.LBB0_213:
	v_lshl_add_u32 v128, s4, 8, v141
	v_ashrrev_i32_e32 v129, 31, v128
	v_lshl_add_u64 v[130:131], v[128:129], 2, s[88:89]
	global_load_dword v136, v[130:131], off
	global_load_dword v236, v[130:131], off offset:64
	global_load_dword v237, v[130:131], off offset:128
	global_load_dword v238, v[130:131], off offset:192
	global_load_dword v239, v[130:131], off offset:512
	global_load_dword v240, v[130:131], off offset:576
	global_load_dword v241, v[130:131], off offset:640
	global_load_dword v242, v[130:131], off offset:704
	v_ashrrev_i32_e32 v129, 1, v140
	s_lshl_b32 s1, s0, 8
	v_readlane_b32 s4, v235, 37
	v_and_b32_e32 v129, -8, v129
	s_or_b32 s1, s4, s1
	v_add_u32_e32 v134, s1, v129
	s_movk_i32 s0, 0x1040
	v_mov_b64_e32 v[132:133], s[52:53]
	v_ashrrev_i32_e32 v135, 31, v134
	v_mad_i64_i32 v[138:139], s[4:5], v128, s0, v[132:133]
	v_or_b32_e32 v140, 16, v128
	v_lshlrev_b64 v[134:135], 1, v[134:135]
	v_ashrrev_i32_e32 v141, 31, v140
	v_lshl_add_u64 v[138:139], v[138:139], 0, v[134:135]
	v_lshl_add_u64 v[142:143], v[140:141], 2, s[88:89]
	s_movk_i32 s1, 0x80
	v_writelane_b32 v235, s1, 45
	s_waitcnt vmcnt(0)
	v_pk_mul_f32 v[126:127], v[126:127], v[136:137] op_sel_hi:[1,0]
	v_pk_mul_f32 v[124:125], v[124:125], v[136:137] op_sel_hi:[1,0]
	v_pk_mul_f32 v[122:123], v[122:123], v[136:137] op_sel_hi:[1,0]
	v_pk_mul_f32 v[120:121], v[120:121], v[136:137] op_sel_hi:[1,0]
	v_pk_mul_f32 v[118:119], v[118:119], v[136:137] op_sel_hi:[1,0]
	v_pk_mul_f32 v[116:117], v[116:117], v[136:137] op_sel_hi:[1,0]
	v_pk_mul_f32 v[144:145], v[114:115], v[136:137] op_sel_hi:[1,0]
	v_pk_mul_f32 v[136:137], v[112:113], v[136:137] op_sel_hi:[1,0]
	v_cvt_pk_bf16_f32 v112, v124, v125
	v_cvt_pk_bf16_f32 v113, v126, v127
	v_cvt_pk_bf16_f32 v114, v120, v121
	v_cvt_pk_bf16_f32 v115, v122, v123
	global_store_dwordx4 v[138:139], v[112:115], off sc1
	s_nop 1
	v_cvt_pk_bf16_f32 v112, v116, v117
	v_cvt_pk_bf16_f32 v113, v118, v119
	v_cvt_pk_bf16_f32 v114, v136, v137
	v_cvt_pk_bf16_f32 v115, v144, v145
	global_store_dwordx4 v[138:139], v[112:115], off offset:256 sc1
	s_nop 1
	v_mad_i64_i32 v[116:117], s[4:5], v140, s0, v[132:133]
	v_or_b32_e32 v114, 32, v128
	v_ashrrev_i32_e32 v115, 31, v114
	v_lshl_add_u64 v[116:117], v[116:117], 0, v[134:135]
	v_lshl_add_u64 v[118:119], v[114:115], 2, s[88:89]
	s_nop 1
	v_mov_b32_e32 v112, v236
	v_pk_mul_f32 v[110:111], v[110:111], v[112:113] op_sel_hi:[1,0]
	v_pk_mul_f32 v[108:109], v[108:109], v[112:113] op_sel_hi:[1,0]
	v_pk_mul_f32 v[106:107], v[106:107], v[112:113] op_sel_hi:[1,0]
	v_pk_mul_f32 v[104:105], v[104:105], v[112:113] op_sel_hi:[1,0]
	v_pk_mul_f32 v[102:103], v[102:103], v[112:113] op_sel_hi:[1,0]
	v_pk_mul_f32 v[100:101], v[100:101], v[112:113] op_sel_hi:[1,0]
	v_pk_mul_f32 v[120:121], v[98:99], v[112:113] op_sel_hi:[1,0]
	v_pk_mul_f32 v[112:113], v[96:97], v[112:113] op_sel_hi:[1,0]
	v_cvt_pk_bf16_f32 v96, v108, v109
	v_cvt_pk_bf16_f32 v97, v110, v111
	v_cvt_pk_bf16_f32 v98, v104, v105
	v_cvt_pk_bf16_f32 v99, v106, v107
	global_store_dwordx4 v[116:117], v[96:99], off sc1
	s_nop 1
	v_cvt_pk_bf16_f32 v96, v100, v101
	v_cvt_pk_bf16_f32 v97, v102, v103
	v_cvt_pk_bf16_f32 v98, v112, v113
	v_cvt_pk_bf16_f32 v99, v120, v121
	global_store_dwordx4 v[116:117], v[96:99], off offset:256 sc1
	s_nop 1
	v_mad_i64_i32 v[100:101], s[4:5], v114, s0, v[132:133]
	v_or_b32_e32 v98, 48, v128
	v_ashrrev_i32_e32 v99, 31, v98
	v_lshl_add_u64 v[100:101], v[100:101], 0, v[134:135]
	v_lshl_add_u64 v[102:103], v[98:99], 2, s[88:89]
	s_nop 1
	v_mov_b32_e32 v96, v237
	v_pk_mul_f32 v[94:95], v[94:95], v[96:97] op_sel_hi:[1,0]
	v_pk_mul_f32 v[92:93], v[92:93], v[96:97] op_sel_hi:[1,0]
	v_pk_mul_f32 v[90:91], v[90:91], v[96:97] op_sel_hi:[1,0]
	v_pk_mul_f32 v[88:89], v[88:89], v[96:97] op_sel_hi:[1,0]
	v_pk_mul_f32 v[82:83], v[82:83], v[96:97] op_sel_hi:[1,0]
	v_pk_mul_f32 v[80:81], v[80:81], v[96:97] op_sel_hi:[1,0]
	v_pk_mul_f32 v[104:105], v[74:75], v[96:97] op_sel_hi:[1,0]
	v_pk_mul_f32 v[96:97], v[72:73], v[96:97] op_sel_hi:[1,0]
	v_cvt_pk_bf16_f32 v72, v92, v93
	v_cvt_pk_bf16_f32 v73, v94, v95
	v_cvt_pk_bf16_f32 v74, v88, v89
	v_cvt_pk_bf16_f32 v75, v90, v91
	global_store_dwordx4 v[100:101], v[72:75], off sc1
	s_nop 1
	v_cvt_pk_bf16_f32 v72, v80, v81
	v_cvt_pk_bf16_f32 v73, v82, v83
	v_cvt_pk_bf16_f32 v74, v96, v97
	v_cvt_pk_bf16_f32 v75, v104, v105
	global_store_dwordx4 v[100:101], v[72:75], off offset:256 sc1
	s_nop 1
	s_nop 1
	v_mov_b32_e32 v72, v238
	v_pk_mul_f32 v[80:81], v[86:87], v[72:73] op_sel_hi:[1,0]
	v_mad_i64_i32 v[74:75], s[4:5], v98, s0, v[132:133]
	v_lshl_add_u64 v[74:75], v[74:75], 0, v[134:135]
	v_pk_mul_f32 v[82:83], v[84:85], v[72:73] op_sel_hi:[1,0]
	v_pk_mul_f32 v[78:79], v[78:79], v[72:73] op_sel_hi:[1,0]
	v_pk_mul_f32 v[76:77], v[76:77], v[72:73] op_sel_hi:[1,0]
	v_pk_mul_f32 v[70:71], v[70:71], v[72:73] op_sel_hi:[1,0]
	v_pk_mul_f32 v[68:69], v[68:69], v[72:73] op_sel_hi:[1,0]
	v_pk_mul_f32 v[84:85], v[66:67], v[72:73] op_sel_hi:[1,0]
	v_pk_mul_f32 v[72:73], v[64:65], v[72:73] op_sel_hi:[1,0]
	v_cvt_pk_bf16_f32 v64, v82, v83
	v_cvt_pk_bf16_f32 v65, v80, v81
	v_cvt_pk_bf16_f32 v66, v76, v77
	v_cvt_pk_bf16_f32 v67, v78, v79
	global_store_dwordx4 v[74:75], v[64:67], off sc1
	s_nop 1
	v_cvt_pk_bf16_f32 v64, v68, v69
	v_cvt_pk_bf16_f32 v65, v70, v71
	v_cvt_pk_bf16_f32 v66, v72, v73
	v_cvt_pk_bf16_f32 v67, v84, v85
	global_store_dwordx4 v[74:75], v[64:67], off offset:256 sc1
	s_nop 1
	s_nop 0
	v_add_u32_e32 v65, 0x80, v128
	v_mad_i64_i32 v[66:67], s[4:5], v65, s0, v[132:133]
	v_lshl_add_u64 v[66:67], v[66:67], 0, v[134:135]
	s_nop 1
	v_mov_b32_e32 v64, v239
	v_pk_mul_f32 v[62:63], v[62:63], v[64:65] op_sel_hi:[1,0]
	v_pk_mul_f32 v[60:61], v[60:61], v[64:65] op_sel_hi:[1,0]
	v_pk_mul_f32 v[58:59], v[58:59], v[64:65] op_sel_hi:[1,0]
	v_pk_mul_f32 v[56:57], v[56:57], v[64:65] op_sel_hi:[1,0]
	v_pk_mul_f32 v[54:55], v[54:55], v[64:65] op_sel_hi:[1,0]
	v_pk_mul_f32 v[52:53], v[52:53], v[64:65] op_sel_hi:[1,0]
	v_pk_mul_f32 v[68:69], v[50:51], v[64:65] op_sel_hi:[1,0]
	v_pk_mul_f32 v[64:65], v[48:49], v[64:65] op_sel_hi:[1,0]
	v_cvt_pk_bf16_f32 v48, v60, v61
	v_cvt_pk_bf16_f32 v49, v62, v63
	v_cvt_pk_bf16_f32 v50, v56, v57
	v_cvt_pk_bf16_f32 v51, v58, v59
	global_store_dwordx4 v[66:67], v[48:51], off sc1
	s_nop 1
	v_cvt_pk_bf16_f32 v48, v52, v53
	v_cvt_pk_bf16_f32 v49, v54, v55
	v_cvt_pk_bf16_f32 v50, v64, v65
	v_cvt_pk_bf16_f32 v51, v68, v69
	global_store_dwordx4 v[66:67], v[48:51], off offset:256 sc1
	s_nop 1
	s_nop 0
	v_add_u32_e32 v49, 0x90, v128
	v_mad_i64_i32 v[50:51], s[4:5], v49, s0, v[132:133]
	v_lshl_add_u64 v[50:51], v[50:51], 0, v[134:135]
	s_nop 1
	v_mov_b32_e32 v48, v240
	v_pk_mul_f32 v[46:47], v[46:47], v[48:49] op_sel_hi:[1,0]
	v_pk_mul_f32 v[44:45], v[44:45], v[48:49] op_sel_hi:[1,0]
	v_pk_mul_f32 v[42:43], v[42:43], v[48:49] op_sel_hi:[1,0]
	v_pk_mul_f32 v[40:41], v[40:41], v[48:49] op_sel_hi:[1,0]
	v_pk_mul_f32 v[38:39], v[38:39], v[48:49] op_sel_hi:[1,0]
	v_pk_mul_f32 v[36:37], v[36:37], v[48:49] op_sel_hi:[1,0]
	v_pk_mul_f32 v[52:53], v[34:35], v[48:49] op_sel_hi:[1,0]
	v_pk_mul_f32 v[48:49], v[32:33], v[48:49] op_sel_hi:[1,0]
	v_cvt_pk_bf16_f32 v32, v44, v45
	v_cvt_pk_bf16_f32 v33, v46, v47
	v_cvt_pk_bf16_f32 v34, v40, v41
	v_cvt_pk_bf16_f32 v35, v42, v43
	global_store_dwordx4 v[50:51], v[32:35], off sc1
	s_nop 1
	v_cvt_pk_bf16_f32 v32, v36, v37
	v_cvt_pk_bf16_f32 v33, v38, v39
	v_cvt_pk_bf16_f32 v34, v48, v49
	v_cvt_pk_bf16_f32 v35, v52, v53
	global_store_dwordx4 v[50:51], v[32:35], off offset:256 sc1
	s_nop 1
	s_nop 0
	v_add_u32_e32 v33, 0xa0, v128
	v_mad_i64_i32 v[34:35], s[4:5], v33, s0, v[132:133]
	v_lshl_add_u64 v[34:35], v[34:35], 0, v[134:135]
	s_nop 1
	v_mov_b32_e32 v32, v241
	v_pk_mul_f32 v[30:31], v[30:31], v[32:33] op_sel_hi:[1,0]
	v_pk_mul_f32 v[28:29], v[28:29], v[32:33] op_sel_hi:[1,0]
	v_pk_mul_f32 v[26:27], v[26:27], v[32:33] op_sel_hi:[1,0]
	v_pk_mul_f32 v[24:25], v[24:25], v[32:33] op_sel_hi:[1,0]
	v_pk_mul_f32 v[22:23], v[22:23], v[32:33] op_sel_hi:[1,0]
	v_pk_mul_f32 v[20:21], v[20:21], v[32:33] op_sel_hi:[1,0]
	v_pk_mul_f32 v[36:37], v[18:19], v[32:33] op_sel_hi:[1,0]
	v_pk_mul_f32 v[32:33], v[16:17], v[32:33] op_sel_hi:[1,0]
	v_cvt_pk_bf16_f32 v16, v28, v29
	v_cvt_pk_bf16_f32 v17, v30, v31
	v_cvt_pk_bf16_f32 v18, v24, v25
	v_cvt_pk_bf16_f32 v19, v26, v27
	global_store_dwordx4 v[34:35], v[16:19], off sc1
	s_nop 1
	v_cvt_pk_bf16_f32 v16, v20, v21
	v_cvt_pk_bf16_f32 v17, v22, v23
	v_cvt_pk_bf16_f32 v18, v32, v33
	v_cvt_pk_bf16_f32 v19, v36, v37
	global_store_dwordx4 v[34:35], v[16:19], off offset:256 sc1
	s_nop 1
	s_nop 0
	v_add_u32_e32 v17, 0xb0, v128
	v_mad_i64_i32 v[18:19], s[0:1], v17, s0, v[132:133]
	v_lshl_add_u64 v[18:19], v[18:19], 0, v[134:135]
	v_readlane_b32 s0, v235, 41
	v_readlane_b32 s1, v235, 42
	s_and_b64 vcc, exec, s[0:1]
	s_nop 1
	v_mov_b32_e32 v16, v242
	v_pk_mul_f32 v[14:15], v[14:15], v[16:17] op_sel_hi:[1,0]
	v_pk_mul_f32 v[12:13], v[12:13], v[16:17] op_sel_hi:[1,0]
	v_pk_mul_f32 v[10:11], v[10:11], v[16:17] op_sel_hi:[1,0]
	v_pk_mul_f32 v[8:9], v[8:9], v[16:17] op_sel_hi:[1,0]
	v_pk_mul_f32 v[6:7], v[6:7], v[16:17] op_sel_hi:[1,0]
	v_pk_mul_f32 v[4:5], v[4:5], v[16:17] op_sel_hi:[1,0]
	v_pk_mul_f32 v[20:21], v[2:3], v[16:17] op_sel_hi:[1,0]
	v_pk_mul_f32 v[16:17], v[0:1], v[16:17] op_sel_hi:[1,0]
	v_cvt_pk_bf16_f32 v0, v12, v13
	v_cvt_pk_bf16_f32 v1, v14, v15
	v_cvt_pk_bf16_f32 v2, v8, v9
	v_cvt_pk_bf16_f32 v3, v10, v11
	global_store_dwordx4 v[18:19], v[0:3], off sc1
	s_nop 1
	v_cvt_pk_bf16_f32 v0, v4, v5
	v_cvt_pk_bf16_f32 v1, v6, v7
	v_cvt_pk_bf16_f32 v2, v16, v17
	v_cvt_pk_bf16_f32 v3, v20, v21
	global_store_dwordx4 v[18:19], v[0:3], off offset:256 sc1
	s_waitcnt vmcnt(0)
	s_barrier
	s_waitcnt vmcnt(0)
	s_barrier
	s_cbranch_vccnz .LBB0_228
	v_mbcnt_lo_u32_b32 v0, -1, 0
	v_mbcnt_hi_u32_b32 v0, -1, v0
	s_nop 0
	v_cmp_eq_u32_e32 vcc, 0, v0
	s_and_saveexec_b64 s[0:1], vcc
	s_cbranch_execz .LBB0_227
	v_mov_b32_e32 v236, 0x3500
	s_movk_i32 s101, 0x4000

ATD0_DONE:
	s_mov_b64 s[6:7], exec
	s_nop 0
	s_waitcnt vmcnt(0)
	s_waitcnt vmcnt(0)
	v_mbcnt_lo_u32_b32 v0, s6, 0
	s_add_u32 s4, s78, 0x3700
	v_mbcnt_hi_u32_b32 v0, s7, v0
	s_addc_u32 s5, s79, 0
	v_cmp_eq_u32_e32 vcc, 0, v0
	s_and_saveexec_b64 s[8:9], vcc
	s_cbranch_execz .LBB0_217
	s_bcnt1_i32_b64 s6, s[6:7]
	v_mov_b32_e32 v0, 0
	v_mov_b32_e32 v1, s6
	global_atomic_add v0, v1, s[4:5]

.LBB0_922:
	v_ashrrev_i32_e32 v128, 1, v140
	v_and_b32_e32 v129, -8, v128
	v_lshl_add_u32 v128, s0, 8, v141
	s_lshl_b32 s0, s4, 8
	v_readlane_b32 s1, v235, 37
	s_or_b32 s0, s1, s0
	v_add_u32_e32 v132, s0, v129
	v_ashrrev_i32_e32 v133, 31, v132
	s_movk_i32 s0, 0x1040
	v_mov_b64_e32 v[130:131], s[52:53]
	v_ashrrev_i32_e32 v129, 31, v128
	v_mad_i64_i32 v[134:135], s[4:5], v128, s0, v[130:131]
	v_lshlrev_b64 v[132:133], 1, v[132:133]
	v_lshl_add_u64 v[136:137], v[134:135], 0, v[132:133]
	v_lshl_add_u64 v[134:135], v[128:129], 2, s[88:89]
	global_load_dword v138, v[134:135], off
	global_load_dword v236, v[134:135], off offset:64
	global_load_dword v237, v[134:135], off offset:128
	global_load_dword v238, v[134:135], off offset:192
	global_load_dword v239, v[134:135], off offset:512
	global_load_dword v240, v[134:135], off offset:576
	global_load_dword v241, v[134:135], off offset:640
	global_load_dword v242, v[134:135], off offset:704
	s_waitcnt vmcnt(0)
	v_pk_mul_f32 v[126:127], v[126:127], v[138:139] op_sel_hi:[1,0]
	v_pk_mul_f32 v[124:125], v[124:125], v[138:139] op_sel_hi:[1,0]
	v_pk_mul_f32 v[140:141], v[122:123], v[138:139] op_sel_hi:[1,0]
	v_pk_mul_f32 v[122:123], v[120:121], v[138:139] op_sel_hi:[1,0]
	v_cvt_pk_bf16_f32 v120, v124, v125
	v_cvt_pk_bf16_f32 v121, v126, v127
	v_pk_mul_f32 v[116:117], v[116:117], v[138:139] op_sel_hi:[1,0]
	v_cvt_pk_bf16_f32 v122, v122, v123
	v_cvt_pk_bf16_f32 v123, v140, v141
	global_store_dwordx4 v[136:137], v[120:123], off sc1
	v_pk_mul_f32 v[118:119], v[118:119], v[138:139] op_sel_hi:[1,0]
	s_nop 0
	v_pk_mul_f32 v[120:121], v[114:115], v[138:139] op_sel_hi:[1,0]
	v_pk_mul_f32 v[114:115], v[112:113], v[138:139] op_sel_hi:[1,0]
	v_cvt_pk_bf16_f32 v112, v116, v117
	v_cvt_pk_bf16_f32 v113, v118, v119
	s_nop 0
	v_cvt_pk_bf16_f32 v114, v114, v115
	v_cvt_pk_bf16_f32 v115, v120, v121
	global_store_dwordx4 v[136:137], v[112:115], off offset:256 sc1
	s_nop 1
	v_or_b32_e32 v112, 16, v128
	v_ashrrev_i32_e32 v113, 31, v112
	v_mad_i64_i32 v[114:115], s[4:5], v112, s0, v[130:131]
	v_lshl_add_u64 v[112:113], v[112:113], 2, s[88:89]
	s_nop 1
	v_lshl_add_u64 v[114:115], v[114:115], 0, v[132:133]
	s_nop 1
	v_mov_b32_e32 v112, v236
	v_pk_mul_f32 v[110:111], v[110:111], v[112:113] op_sel_hi:[1,0]
	v_pk_mul_f32 v[108:109], v[108:109], v[112:113] op_sel_hi:[1,0]
	v_pk_mul_f32 v[116:117], v[106:107], v[112:113] op_sel_hi:[1,0]
	v_pk_mul_f32 v[106:107], v[104:105], v[112:113] op_sel_hi:[1,0]
	v_cvt_pk_bf16_f32 v104, v108, v109
	v_cvt_pk_bf16_f32 v105, v110, v111
	v_pk_mul_f32 v[100:101], v[100:101], v[112:113] op_sel_hi:[1,0]
	v_cvt_pk_bf16_f32 v106, v106, v107
	v_cvt_pk_bf16_f32 v107, v116, v117
	global_store_dwordx4 v[114:115], v[104:107], off sc1
	v_pk_mul_f32 v[102:103], v[102:103], v[112:113] op_sel_hi:[1,0]
	s_nop 0
	v_pk_mul_f32 v[104:105], v[98:99], v[112:113] op_sel_hi:[1,0]
	v_pk_mul_f32 v[98:99], v[96:97], v[112:113] op_sel_hi:[1,0]
	v_cvt_pk_bf16_f32 v96, v100, v101
	v_cvt_pk_bf16_f32 v97, v102, v103
	s_nop 0
	v_cvt_pk_bf16_f32 v98, v98, v99
	v_cvt_pk_bf16_f32 v99, v104, v105
	global_store_dwordx4 v[114:115], v[96:99], off offset:256 sc1
	s_nop 1
	v_or_b32_e32 v96, 32, v128
	v_ashrrev_i32_e32 v97, 31, v96
	v_mad_i64_i32 v[98:99], s[4:5], v96, s0, v[130:131]
	v_lshl_add_u64 v[96:97], v[96:97], 2, s[88:89]
	s_nop 1
	v_lshl_add_u64 v[98:99], v[98:99], 0, v[132:133]
	s_nop 1
	v_mov_b32_e32 v96, v237
	v_pk_mul_f32 v[94:95], v[94:95], v[96:97] op_sel_hi:[1,0]
	v_pk_mul_f32 v[92:93], v[92:93], v[96:97] op_sel_hi:[1,0]
	v_pk_mul_f32 v[100:101], v[90:91], v[96:97] op_sel_hi:[1,0]
	v_pk_mul_f32 v[90:91], v[88:89], v[96:97] op_sel_hi:[1,0]
	v_cvt_pk_bf16_f32 v88, v92, v93
	v_cvt_pk_bf16_f32 v89, v94, v95
	v_pk_mul_f32 v[84:85], v[84:85], v[96:97] op_sel_hi:[1,0]
	v_cvt_pk_bf16_f32 v90, v90, v91
	v_cvt_pk_bf16_f32 v91, v100, v101
	global_store_dwordx4 v[98:99], v[88:91], off sc1
	v_pk_mul_f32 v[86:87], v[86:87], v[96:97] op_sel_hi:[1,0]
	s_nop 0
	v_pk_mul_f32 v[88:89], v[82:83], v[96:97] op_sel_hi:[1,0]
	v_pk_mul_f32 v[82:83], v[80:81], v[96:97] op_sel_hi:[1,0]
	v_cvt_pk_bf16_f32 v80, v84, v85
	v_cvt_pk_bf16_f32 v81, v86, v87
	s_nop 0
	v_cvt_pk_bf16_f32 v82, v82, v83
	v_cvt_pk_bf16_f32 v83, v88, v89
	global_store_dwordx4 v[98:99], v[80:83], off offset:256 sc1
	s_nop 1
	v_or_b32_e32 v80, 48, v128
	v_ashrrev_i32_e32 v81, 31, v80
	v_mad_i64_i32 v[82:83], s[4:5], v80, s0, v[130:131]
	v_lshl_add_u64 v[80:81], v[80:81], 2, s[88:89]
	s_nop 1
	v_lshl_add_u64 v[82:83], v[82:83], 0, v[132:133]
	s_nop 1
	v_mov_b32_e32 v80, v238
	v_pk_mul_f32 v[78:79], v[78:79], v[80:81] op_sel_hi:[1,0]
	v_pk_mul_f32 v[76:77], v[76:77], v[80:81] op_sel_hi:[1,0]
	v_pk_mul_f32 v[84:85], v[74:75], v[80:81] op_sel_hi:[1,0]
	v_pk_mul_f32 v[74:75], v[72:73], v[80:81] op_sel_hi:[1,0]
	v_cvt_pk_bf16_f32 v72, v76, v77
	v_cvt_pk_bf16_f32 v73, v78, v79
	v_pk_mul_f32 v[70:71], v[70:71], v[80:81] op_sel_hi:[1,0]
	v_cvt_pk_bf16_f32 v74, v74, v75
	v_cvt_pk_bf16_f32 v75, v84, v85
	global_store_dwordx4 v[82:83], v[72:75], off sc1
	v_pk_mul_f32 v[68:69], v[68:69], v[80:81] op_sel_hi:[1,0]
	s_nop 0
	v_pk_mul_f32 v[72:73], v[66:67], v[80:81] op_sel_hi:[1,0]
	v_pk_mul_f32 v[66:67], v[64:65], v[80:81] op_sel_hi:[1,0]
	v_cvt_pk_bf16_f32 v64, v68, v69
	v_cvt_pk_bf16_f32 v65, v70, v71
	s_nop 0
	v_cvt_pk_bf16_f32 v66, v66, v67
	v_cvt_pk_bf16_f32 v67, v72, v73
	global_store_dwordx4 v[82:83], v[64:67], off offset:256 sc1
	s_nop 1
	s_nop 1
	v_mov_b32_e32 v66, v239
	v_pk_mul_f32 v[62:63], v[62:63], v[66:67] op_sel_hi:[1,0]
	v_add_u32_e32 v64, 0x80, v128
	v_mad_i64_i32 v[64:65], s[4:5], v64, s0, v[130:131]
	v_lshl_add_u64 v[64:65], v[64:65], 0, v[132:133]
	v_pk_mul_f32 v[60:61], v[60:61], v[66:67] op_sel_hi:[1,0]
	v_pk_mul_f32 v[68:69], v[58:59], v[66:67] op_sel_hi:[1,0]
	v_pk_mul_f32 v[58:59], v[56:57], v[66:67] op_sel_hi:[1,0]
	v_cvt_pk_bf16_f32 v56, v60, v61
	v_cvt_pk_bf16_f32 v57, v62, v63
	v_pk_mul_f32 v[54:55], v[54:55], v[66:67] op_sel_hi:[1,0]
	v_cvt_pk_bf16_f32 v58, v58, v59
	v_cvt_pk_bf16_f32 v59, v68, v69
	global_store_dwordx4 v[64:65], v[56:59], off sc1
	v_pk_mul_f32 v[52:53], v[52:53], v[66:67] op_sel_hi:[1,0]
	s_nop 0
	v_pk_mul_f32 v[56:57], v[50:51], v[66:67] op_sel_hi:[1,0]
	v_pk_mul_f32 v[50:51], v[48:49], v[66:67] op_sel_hi:[1,0]
	v_cvt_pk_bf16_f32 v48, v52, v53
	v_cvt_pk_bf16_f32 v49, v54, v55
	s_nop 0
	v_cvt_pk_bf16_f32 v50, v50, v51
	v_cvt_pk_bf16_f32 v51, v56, v57
	global_store_dwordx4 v[64:65], v[48:51], off offset:256 sc1
	s_nop 1
	s_nop 1
	v_mov_b32_e32 v50, v240
	v_pk_mul_f32 v[46:47], v[46:47], v[50:51] op_sel_hi:[1,0]
	v_add_u32_e32 v48, 0x90, v128
	v_mad_i64_i32 v[48:49], s[4:5], v48, s0, v[130:131]
	v_lshl_add_u64 v[48:49], v[48:49], 0, v[132:133]
	v_pk_mul_f32 v[44:45], v[44:45], v[50:51] op_sel_hi:[1,0]
	v_pk_mul_f32 v[52:53], v[42:43], v[50:51] op_sel_hi:[1,0]
	v_pk_mul_f32 v[42:43], v[40:41], v[50:51] op_sel_hi:[1,0]
	v_cvt_pk_bf16_f32 v40, v44, v45
	v_cvt_pk_bf16_f32 v41, v46, v47
	v_pk_mul_f32 v[38:39], v[38:39], v[50:51] op_sel_hi:[1,0]
	v_cvt_pk_bf16_f32 v42, v42, v43
	v_cvt_pk_bf16_f32 v43, v52, v53
	global_store_dwordx4 v[48:49], v[40:43], off sc1
	v_pk_mul_f32 v[36:37], v[36:37], v[50:51] op_sel_hi:[1,0]
	s_nop 0
	v_pk_mul_f32 v[40:41], v[34:35], v[50:51] op_sel_hi:[1,0]
	v_pk_mul_f32 v[34:35], v[32:33], v[50:51] op_sel_hi:[1,0]
	v_cvt_pk_bf16_f32 v32, v36, v37
	v_cvt_pk_bf16_f32 v33, v38, v39
	s_nop 0
	v_cvt_pk_bf16_f32 v34, v34, v35
	v_cvt_pk_bf16_f32 v35, v40, v41
	global_store_dwordx4 v[48:49], v[32:35], off offset:256 sc1
	s_nop 1
	s_nop 1
	v_mov_b32_e32 v34, v241
	v_pk_mul_f32 v[30:31], v[30:31], v[34:35] op_sel_hi:[1,0]
	v_add_u32_e32 v32, 0xa0, v128
	v_mad_i64_i32 v[32:33], s[4:5], v32, s0, v[130:131]
	v_lshl_add_u64 v[32:33], v[32:33], 0, v[132:133]
	v_pk_mul_f32 v[28:29], v[28:29], v[34:35] op_sel_hi:[1,0]
	v_pk_mul_f32 v[36:37], v[26:27], v[34:35] op_sel_hi:[1,0]
	v_pk_mul_f32 v[26:27], v[24:25], v[34:35] op_sel_hi:[1,0]
	v_cvt_pk_bf16_f32 v24, v28, v29
	v_cvt_pk_bf16_f32 v25, v30, v31
	v_pk_mul_f32 v[22:23], v[22:23], v[34:35] op_sel_hi:[1,0]
	v_cvt_pk_bf16_f32 v26, v26, v27
	v_cvt_pk_bf16_f32 v27, v36, v37
	global_store_dwordx4 v[32:33], v[24:27], off sc1
	v_pk_mul_f32 v[20:21], v[20:21], v[34:35] op_sel_hi:[1,0]
	s_nop 0
	v_pk_mul_f32 v[24:25], v[18:19], v[34:35] op_sel_hi:[1,0]
	v_pk_mul_f32 v[18:19], v[16:17], v[34:35] op_sel_hi:[1,0]
	v_cvt_pk_bf16_f32 v16, v20, v21
	v_cvt_pk_bf16_f32 v17, v22, v23
	s_nop 0
	v_cvt_pk_bf16_f32 v18, v18, v19
	v_cvt_pk_bf16_f32 v19, v24, v25
	global_store_dwordx4 v[32:33], v[16:19], off offset:256 sc1
	s_nop 1
	s_nop 1
	v_mov_b32_e32 v18, v242
	v_pk_mul_f32 v[14:15], v[14:15], v[18:19] op_sel_hi:[1,0]
	v_add_u32_e32 v16, 0xb0, v128
	v_mad_i64_i32 v[16:17], s[0:1], v16, s0, v[130:131]
	v_lshl_add_u64 v[16:17], v[16:17], 0, v[132:133]
	v_pk_mul_f32 v[12:13], v[12:13], v[18:19] op_sel_hi:[1,0]
	v_pk_mul_f32 v[20:21], v[10:11], v[18:19] op_sel_hi:[1,0]
	v_pk_mul_f32 v[10:11], v[8:9], v[18:19] op_sel_hi:[1,0]
	v_cvt_pk_bf16_f32 v8, v12, v13
	v_cvt_pk_bf16_f32 v9, v14, v15
	v_pk_mul_f32 v[6:7], v[6:7], v[18:19] op_sel_hi:[1,0]
	v_cvt_pk_bf16_f32 v10, v10, v11
	v_cvt_pk_bf16_f32 v11, v20, v21
	global_store_dwordx4 v[16:17], v[8:11], off sc1
	v_pk_mul_f32 v[4:5], v[4:5], v[18:19] op_sel_hi:[1,0]
	v_readlane_b32 s0, v235, 41
	v_pk_mul_f32 v[8:9], v[2:3], v[18:19] op_sel_hi:[1,0]
	v_pk_mul_f32 v[2:3], v[0:1], v[18:19] op_sel_hi:[1,0]
	v_cvt_pk_bf16_f32 v0, v4, v5
	v_cvt_pk_bf16_f32 v1, v6, v7
	v_readlane_b32 s1, v235, 42
	v_cvt_pk_bf16_f32 v2, v2, v3
	v_cvt_pk_bf16_f32 v3, v8, v9
	global_store_dwordx4 v[16:17], v[0:3], off offset:256 sc1
	s_waitcnt vmcnt(0)
	s_barrier
	s_waitcnt vmcnt(0)
	s_and_b64 vcc, exec, s[0:1]
	s_barrier
	s_cbranch_vccnz .LBB0_936
	v_mbcnt_lo_u32_b32 v0, -1, 0
	v_mbcnt_hi_u32_b32 v0, -1, v0
	s_nop 0
	v_cmp_eq_u32_e32 vcc, 0, v0
	s_and_saveexec_b64 s[0:1], vcc
	s_cbranch_execz .LBB0_935
	v_mov_b32_e32 v236, 0x3500
	s_movk_i32 s101, 0x4000

ATD1_DONE:
	s_mov_b64 s[6:7], exec
	s_nop 0
	s_waitcnt vmcnt(0)
	s_waitcnt vmcnt(0)
	v_mbcnt_lo_u32_b32 v0, s6, 0
	s_add_u32 s4, s78, 0x3800
	v_mbcnt_hi_u32_b32 v0, s7, v0
	s_addc_u32 s5, s79, 0
	v_cmp_eq_u32_e32 vcc, 0, v0
	s_and_saveexec_b64 s[8:9], vcc
	s_cbranch_execz .LBB0_926
	s_bcnt1_i32_b64 s6, s[6:7]
	v_mov_b32_e32 v0, 0
	v_mov_b32_e32 v1, s6
	global_atomic_add v0, v1, s[4:5]

ATD2_DONE:
	s_mov_b64 s[6:7], exec
	s_nop 0
	s_waitcnt vmcnt(0)
	s_waitcnt vmcnt(0)
	v_mbcnt_lo_u32_b32 v0, s6, 0
	s_add_u32 s4, s78, 0x3900
	v_mbcnt_hi_u32_b32 v0, s7, v0
	s_addc_u32 s5, s79, 0
	v_cmp_eq_u32_e32 vcc, 0, v0
	s_and_saveexec_b64 s[8:9], vcc
	s_cbranch_execz .LBB0_1635
	s_bcnt1_i32_b64 s6, s[6:7]
	v_mov_b32_e32 v0, 0
	v_mov_b32_e32 v1, s6
	global_atomic_add v0, v1, s[4:5]

.LBB0_2340:
	v_lshl_add_u32 v128, s4, 8, v141
	v_ashrrev_i32_e32 v129, 31, v128
	v_lshl_add_u64 v[130:131], v[128:129], 2, s[88:89]
	global_load_dword v136, v[130:131], off
	global_load_dword v236, v[130:131], off offset:64
	global_load_dword v237, v[130:131], off offset:128
	global_load_dword v238, v[130:131], off offset:192
	global_load_dword v239, v[130:131], off offset:512
	global_load_dword v240, v[130:131], off offset:576
	global_load_dword v241, v[130:131], off offset:640
	global_load_dword v242, v[130:131], off offset:704
	v_ashrrev_i32_e32 v129, 1, v140
	s_lshl_b32 s1, s0, 8
	v_readlane_b32 s4, v235, 37
	v_and_b32_e32 v129, -8, v129
	s_or_b32 s1, s4, s1
	v_add_u32_e32 v134, s1, v129
	s_movk_i32 s0, 0x1040
	v_mov_b64_e32 v[132:133], s[52:53]
	v_ashrrev_i32_e32 v135, 31, v134
	v_mad_i64_i32 v[138:139], s[4:5], v128, s0, v[132:133]
	v_or_b32_e32 v140, 16, v128
	v_lshlrev_b64 v[134:135], 1, v[134:135]
	v_ashrrev_i32_e32 v141, 31, v140
	v_lshl_add_u64 v[138:139], v[138:139], 0, v[134:135]
	v_lshl_add_u64 v[142:143], v[140:141], 2, s[88:89]
	s_waitcnt vmcnt(0)
	v_pk_mul_f32 v[126:127], v[126:127], v[136:137] op_sel_hi:[1,0]
	v_pk_mul_f32 v[124:125], v[124:125], v[136:137] op_sel_hi:[1,0]
	v_pk_mul_f32 v[122:123], v[122:123], v[136:137] op_sel_hi:[1,0]
	v_pk_mul_f32 v[120:121], v[120:121], v[136:137] op_sel_hi:[1,0]
	v_pk_mul_f32 v[118:119], v[118:119], v[136:137] op_sel_hi:[1,0]
	v_pk_mul_f32 v[116:117], v[116:117], v[136:137] op_sel_hi:[1,0]
	v_pk_mul_f32 v[144:145], v[114:115], v[136:137] op_sel_hi:[1,0]
	v_pk_mul_f32 v[136:137], v[112:113], v[136:137] op_sel_hi:[1,0]
	v_cvt_pk_bf16_f32 v112, v124, v125
	v_cvt_pk_bf16_f32 v113, v126, v127
	v_cvt_pk_bf16_f32 v114, v120, v121
	v_cvt_pk_bf16_f32 v115, v122, v123
	global_store_dwordx4 v[138:139], v[112:115], off sc1
	s_nop 1
	v_cvt_pk_bf16_f32 v112, v116, v117
	v_cvt_pk_bf16_f32 v113, v118, v119
	v_cvt_pk_bf16_f32 v114, v136, v137
	v_cvt_pk_bf16_f32 v115, v144, v145
	global_store_dwordx4 v[138:139], v[112:115], off offset:256 sc1
	s_nop 1
	v_mad_i64_i32 v[116:117], s[4:5], v140, s0, v[132:133]
	v_or_b32_e32 v114, 32, v128
	v_ashrrev_i32_e32 v115, 31, v114
	v_lshl_add_u64 v[116:117], v[116:117], 0, v[134:135]
	v_lshl_add_u64 v[118:119], v[114:115], 2, s[88:89]
	s_nop 1
	v_mov_b32_e32 v112, v236
	v_pk_mul_f32 v[110:111], v[110:111], v[112:113] op_sel_hi:[1,0]
	v_pk_mul_f32 v[108:109], v[108:109], v[112:113] op_sel_hi:[1,0]
	v_pk_mul_f32 v[106:107], v[106:107], v[112:113] op_sel_hi:[1,0]
	v_pk_mul_f32 v[104:105], v[104:105], v[112:113] op_sel_hi:[1,0]
	v_pk_mul_f32 v[102:103], v[102:103], v[112:113] op_sel_hi:[1,0]
	v_pk_mul_f32 v[100:101], v[100:101], v[112:113] op_sel_hi:[1,0]
	v_pk_mul_f32 v[120:121], v[98:99], v[112:113] op_sel_hi:[1,0]
	v_pk_mul_f32 v[112:113], v[96:97], v[112:113] op_sel_hi:[1,0]
	v_cvt_pk_bf16_f32 v96, v108, v109
	v_cvt_pk_bf16_f32 v97, v110, v111
	v_cvt_pk_bf16_f32 v98, v104, v105
	v_cvt_pk_bf16_f32 v99, v106, v107
	global_store_dwordx4 v[116:117], v[96:99], off sc1
	s_nop 1
	v_cvt_pk_bf16_f32 v96, v100, v101
	v_cvt_pk_bf16_f32 v97, v102, v103
	v_cvt_pk_bf16_f32 v98, v112, v113
	v_cvt_pk_bf16_f32 v99, v120, v121
	global_store_dwordx4 v[116:117], v[96:99], off offset:256 sc1
	s_nop 1
	v_mad_i64_i32 v[100:101], s[4:5], v114, s0, v[132:133]
	v_or_b32_e32 v98, 48, v128
	v_ashrrev_i32_e32 v99, 31, v98
	v_lshl_add_u64 v[100:101], v[100:101], 0, v[134:135]
	v_lshl_add_u64 v[102:103], v[98:99], 2, s[88:89]
	s_nop 1
	v_mov_b32_e32 v96, v237
	v_pk_mul_f32 v[94:95], v[94:95], v[96:97] op_sel_hi:[1,0]
	v_pk_mul_f32 v[92:93], v[92:93], v[96:97] op_sel_hi:[1,0]
	v_pk_mul_f32 v[90:91], v[90:91], v[96:97] op_sel_hi:[1,0]
	v_pk_mul_f32 v[88:89], v[88:89], v[96:97] op_sel_hi:[1,0]
	v_pk_mul_f32 v[82:83], v[82:83], v[96:97] op_sel_hi:[1,0]
	v_pk_mul_f32 v[80:81], v[80:81], v[96:97] op_sel_hi:[1,0]
	v_pk_mul_f32 v[104:105], v[74:75], v[96:97] op_sel_hi:[1,0]
	v_pk_mul_f32 v[96:97], v[72:73], v[96:97] op_sel_hi:[1,0]
	v_cvt_pk_bf16_f32 v72, v92, v93
	v_cvt_pk_bf16_f32 v73, v94, v95
	v_cvt_pk_bf16_f32 v74, v88, v89
	v_cvt_pk_bf16_f32 v75, v90, v91
	global_store_dwordx4 v[100:101], v[72:75], off sc1
	s_nop 1
	v_cvt_pk_bf16_f32 v72, v80, v81
	v_cvt_pk_bf16_f32 v73, v82, v83
	v_cvt_pk_bf16_f32 v74, v96, v97
	v_cvt_pk_bf16_f32 v75, v104, v105
	global_store_dwordx4 v[100:101], v[72:75], off offset:256 sc1
	s_nop 1
	s_nop 1
	v_mov_b32_e32 v72, v238
	v_pk_mul_f32 v[80:81], v[86:87], v[72:73] op_sel_hi:[1,0]
	v_mad_i64_i32 v[74:75], s[4:5], v98, s0, v[132:133]
	v_lshl_add_u64 v[74:75], v[74:75], 0, v[134:135]
	v_pk_mul_f32 v[82:83], v[84:85], v[72:73] op_sel_hi:[1,0]
	v_pk_mul_f32 v[78:79], v[78:79], v[72:73] op_sel_hi:[1,0]
	v_pk_mul_f32 v[76:77], v[76:77], v[72:73] op_sel_hi:[1,0]
	v_pk_mul_f32 v[70:71], v[70:71], v[72:73] op_sel_hi:[1,0]
	v_pk_mul_f32 v[68:69], v[68:69], v[72:73] op_sel_hi:[1,0]
	v_pk_mul_f32 v[84:85], v[66:67], v[72:73] op_sel_hi:[1,0]
	v_pk_mul_f32 v[72:73], v[64:65], v[72:73] op_sel_hi:[1,0]
	v_cvt_pk_bf16_f32 v64, v82, v83
	v_cvt_pk_bf16_f32 v65, v80, v81
	v_cvt_pk_bf16_f32 v66, v76, v77
	v_cvt_pk_bf16_f32 v67, v78, v79
	global_store_dwordx4 v[74:75], v[64:67], off sc1
	s_nop 1
	v_cvt_pk_bf16_f32 v64, v68, v69
	v_cvt_pk_bf16_f32 v65, v70, v71
	v_cvt_pk_bf16_f32 v66, v72, v73
	v_cvt_pk_bf16_f32 v67, v84, v85
	global_store_dwordx4 v[74:75], v[64:67], off offset:256 sc1
	s_nop 1
	s_nop 0
	v_add_u32_e32 v65, 0x80, v128
	v_mad_i64_i32 v[66:67], s[4:5], v65, s0, v[132:133]
	v_lshl_add_u64 v[66:67], v[66:67], 0, v[134:135]
	s_nop 1
	v_mov_b32_e32 v64, v239
	v_pk_mul_f32 v[62:63], v[62:63], v[64:65] op_sel_hi:[1,0]
	v_pk_mul_f32 v[60:61], v[60:61], v[64:65] op_sel_hi:[1,0]
	v_pk_mul_f32 v[58:59], v[58:59], v[64:65] op_sel_hi:[1,0]
	v_pk_mul_f32 v[56:57], v[56:57], v[64:65] op_sel_hi:[1,0]
	v_pk_mul_f32 v[54:55], v[54:55], v[64:65] op_sel_hi:[1,0]
	v_pk_mul_f32 v[52:53], v[52:53], v[64:65] op_sel_hi:[1,0]
	v_pk_mul_f32 v[68:69], v[50:51], v[64:65] op_sel_hi:[1,0]
	v_pk_mul_f32 v[64:65], v[48:49], v[64:65] op_sel_hi:[1,0]
	v_cvt_pk_bf16_f32 v48, v60, v61
	v_cvt_pk_bf16_f32 v49, v62, v63
	v_cvt_pk_bf16_f32 v50, v56, v57
	v_cvt_pk_bf16_f32 v51, v58, v59
	global_store_dwordx4 v[66:67], v[48:51], off sc1
	s_nop 1
	v_cvt_pk_bf16_f32 v48, v52, v53
	v_cvt_pk_bf16_f32 v49, v54, v55
	v_cvt_pk_bf16_f32 v50, v64, v65
	v_cvt_pk_bf16_f32 v51, v68, v69
	global_store_dwordx4 v[66:67], v[48:51], off offset:256 sc1
	s_nop 1
	s_nop 0
	v_add_u32_e32 v49, 0x90, v128
	v_mad_i64_i32 v[50:51], s[4:5], v49, s0, v[132:133]
	v_lshl_add_u64 v[50:51], v[50:51], 0, v[134:135]
	s_nop 1
	v_mov_b32_e32 v48, v240
	v_pk_mul_f32 v[46:47], v[46:47], v[48:49] op_sel_hi:[1,0]
	v_pk_mul_f32 v[44:45], v[44:45], v[48:49] op_sel_hi:[1,0]
	v_pk_mul_f32 v[42:43], v[42:43], v[48:49] op_sel_hi:[1,0]
	v_pk_mul_f32 v[40:41], v[40:41], v[48:49] op_sel_hi:[1,0]
	v_pk_mul_f32 v[38:39], v[38:39], v[48:49] op_sel_hi:[1,0]
	v_pk_mul_f32 v[36:37], v[36:37], v[48:49] op_sel_hi:[1,0]
	v_pk_mul_f32 v[52:53], v[34:35], v[48:49] op_sel_hi:[1,0]
	v_pk_mul_f32 v[48:49], v[32:33], v[48:49] op_sel_hi:[1,0]
	v_cvt_pk_bf16_f32 v32, v44, v45
	v_cvt_pk_bf16_f32 v33, v46, v47
	v_cvt_pk_bf16_f32 v34, v40, v41
	v_cvt_pk_bf16_f32 v35, v42, v43
	global_store_dwordx4 v[50:51], v[32:35], off sc1
	s_nop 1
	v_cvt_pk_bf16_f32 v32, v36, v37
	v_cvt_pk_bf16_f32 v33, v38, v39
	v_cvt_pk_bf16_f32 v34, v48, v49
	v_cvt_pk_bf16_f32 v35, v52, v53
	global_store_dwordx4 v[50:51], v[32:35], off offset:256 sc1
	s_nop 1
	s_nop 0
	v_add_u32_e32 v33, 0xa0, v128
	v_mad_i64_i32 v[34:35], s[4:5], v33, s0, v[132:133]
	v_lshl_add_u64 v[34:35], v[34:35], 0, v[134:135]
	s_nop 1
	v_mov_b32_e32 v32, v241
	v_pk_mul_f32 v[30:31], v[30:31], v[32:33] op_sel_hi:[1,0]
	v_pk_mul_f32 v[28:29], v[28:29], v[32:33] op_sel_hi:[1,0]
	v_pk_mul_f32 v[26:27], v[26:27], v[32:33] op_sel_hi:[1,0]
	v_pk_mul_f32 v[24:25], v[24:25], v[32:33] op_sel_hi:[1,0]
	v_pk_mul_f32 v[22:23], v[22:23], v[32:33] op_sel_hi:[1,0]
	v_pk_mul_f32 v[20:21], v[20:21], v[32:33] op_sel_hi:[1,0]
	v_pk_mul_f32 v[36:37], v[18:19], v[32:33] op_sel_hi:[1,0]
	v_pk_mul_f32 v[32:33], v[16:17], v[32:33] op_sel_hi:[1,0]
	v_cvt_pk_bf16_f32 v16, v28, v29
	v_cvt_pk_bf16_f32 v17, v30, v31
	v_cvt_pk_bf16_f32 v18, v24, v25
	v_cvt_pk_bf16_f32 v19, v26, v27
	global_store_dwordx4 v[34:35], v[16:19], off sc1
	s_nop 1
	v_cvt_pk_bf16_f32 v16, v20, v21
	v_cvt_pk_bf16_f32 v17, v22, v23
	v_cvt_pk_bf16_f32 v18, v32, v33
	v_cvt_pk_bf16_f32 v19, v36, v37
	global_store_dwordx4 v[34:35], v[16:19], off offset:256 sc1
	s_nop 1
	s_nop 0
	v_add_u32_e32 v17, 0xb0, v128
	v_mad_i64_i32 v[18:19], s[0:1], v17, s0, v[132:133]
	v_lshl_add_u64 v[18:19], v[18:19], 0, v[134:135]
	v_readlane_b32 s0, v235, 41
	v_readlane_b32 s1, v235, 42
	s_and_b64 vcc, exec, s[0:1]
	s_nop 1
	v_mov_b32_e32 v16, v242
	v_pk_mul_f32 v[14:15], v[14:15], v[16:17] op_sel_hi:[1,0]
	v_pk_mul_f32 v[12:13], v[12:13], v[16:17] op_sel_hi:[1,0]
	v_pk_mul_f32 v[10:11], v[10:11], v[16:17] op_sel_hi:[1,0]
	v_pk_mul_f32 v[8:9], v[8:9], v[16:17] op_sel_hi:[1,0]
	v_pk_mul_f32 v[6:7], v[6:7], v[16:17] op_sel_hi:[1,0]
	v_pk_mul_f32 v[4:5], v[4:5], v[16:17] op_sel_hi:[1,0]
	v_pk_mul_f32 v[20:21], v[2:3], v[16:17] op_sel_hi:[1,0]
	v_pk_mul_f32 v[16:17], v[0:1], v[16:17] op_sel_hi:[1,0]
	v_cvt_pk_bf16_f32 v0, v12, v13
	v_cvt_pk_bf16_f32 v1, v14, v15
	v_cvt_pk_bf16_f32 v2, v8, v9
	v_cvt_pk_bf16_f32 v3, v10, v11
	global_store_dwordx4 v[18:19], v[0:3], off sc1
	s_nop 1
	v_cvt_pk_bf16_f32 v0, v4, v5
	v_cvt_pk_bf16_f32 v1, v6, v7
	v_cvt_pk_bf16_f32 v2, v16, v17
	v_cvt_pk_bf16_f32 v3, v20, v21
	global_store_dwordx4 v[18:19], v[0:3], off offset:256 sc1
	s_waitcnt vmcnt(0)
	s_barrier
	s_waitcnt vmcnt(0)
	s_barrier
	s_cbranch_vccnz .LBB0_2354
	v_mbcnt_lo_u32_b32 v0, -1, 0
	v_mbcnt_hi_u32_b32 v0, -1, v0
	s_nop 0
	v_cmp_eq_u32_e32 vcc, 0, v0
	s_and_saveexec_b64 s[0:1], vcc
	s_cbranch_execz .LBB0_2353
	v_mov_b32_e32 v236, 0x3500
	s_movk_i32 s101, 0x4000

ATD3_DONE:
	s_mov_b64 s[6:7], exec
	s_nop 0
	s_waitcnt vmcnt(0)
	s_waitcnt vmcnt(0)
	v_mbcnt_lo_u32_b32 v0, s6, 0
	s_add_u32 s4, s78, 0x3a00
	v_mbcnt_hi_u32_b32 v0, s7, v0
	s_addc_u32 s5, s79, 0
	v_cmp_eq_u32_e32 vcc, 0, v0
	s_and_saveexec_b64 s[8:9], vcc
	s_cbranch_execz .LBB0_2344
	s_bcnt1_i32_b64 s6, s[6:7]
	v_mov_b32_e32 v0, 0
	v_mov_b32_e32 v1, s6
	global_atomic_add v0, v1, s[4:5]
